# ln_first: all eight modulation loads of a row issued with the row loads, so no wait sits behind a store
# speedup vs baseline: 1.0093x; 1.0093x over previous
.LBB0_683:
	s_or_b64 exec, exec, s[14:15]
	v_lshl_add_u64 v[16:17], v[16:17], 0, v[0:1]
	global_load_dwordx4 v[24:27], v[16:17], off
	global_load_dwordx4 v[28:31], v[16:17], off offset:1024
	global_load_dwordx4 v[32:35], v[16:17], off offset:2048
	global_load_dwordx4 v[36:39], v[16:17], off offset:3072
	s_load_dwordx2 s[14:15], s[54:55], 0x130
	v_min_i32_e32 v13, 0x8000, v4
	v_ashrrev_i32_e32 v13, 13, v13
	v_mul_hi_i32_i24_e32 v17, 0x6000, v13
	v_mul_i32_i24_e32 v16, 0x6000, v13
	s_waitcnt lgkmcnt(0)
	v_lshl_add_u64 v[16:17], s[14:15], 0, v[16:17]
	s_mov_b64 s[14:15], 0x1000
	v_lshl_add_u64 v[48:49], v[16:17], 0, s[14:15]
	v_lshl_add_u64 v[40:41], v[48:49], 0, v[0:1]
	global_load_dwordx4 v[40:43], v[40:41], off
	v_lshl_add_u64 v[50:51], v[16:17], 0, v[0:1]
	global_load_dwordx4 v[44:47], v[50:51], off
	v_mov_b32_e32 v97, v1
	v_mov_b32_e32 v96, v8
	v_lshl_add_u64 v[90:91], v[48:49], 0, v[96:97]
	global_load_dwordx4 v[66:69], v[90:91], off
	v_mov_b32_e32 v96, v10
	v_lshl_add_u64 v[92:93], v[48:49], 0, v[96:97]
	global_load_dwordx4 v[70:73], v[92:93], off
	v_mov_b32_e32 v96, v12
	v_lshl_add_u64 v[94:95], v[48:49], 0, v[96:97]
	global_load_dwordx4 v[74:77], v[94:95], off
	global_load_dwordx4 v[78:81], v[50:51], off offset:1024
	global_load_dwordx4 v[82:85], v[50:51], off offset:2048
	global_load_dwordx4 v[86:89], v[50:51], off offset:3072
	v_lshlrev_b64 v[14:15], 11, v[14:15]
	v_lshl_add_u64 v[4:5], v[4:5], 0, s[8:9]
	s_mov_b32 s1, 0x83ff
	v_lshl_add_u64 v[6:7], v[6:7], 0, s[10:11]
	s_waitcnt vmcnt(11)
	v_add_f32_e32 v9, 0, v24
	v_add_f32_e32 v9, v25, v9
	v_add_f32_e32 v9, v26, v9
	v_add_f32_e32 v9, v27, v9
	s_waitcnt vmcnt(10)
	v_add_f32_e32 v9, v28, v9
	v_add_f32_e32 v9, v29, v9
	v_add_f32_e32 v9, v30, v9
	v_add_f32_e32 v9, v31, v9
	s_waitcnt vmcnt(9)
	v_add_f32_e32 v9, v32, v9
	v_add_f32_e32 v9, v33, v9
	v_add_f32_e32 v9, v34, v9
	v_add_f32_e32 v9, v35, v9
	s_waitcnt vmcnt(8)
	v_add_f32_e32 v9, v36, v9
	v_add_f32_e32 v9, v37, v9
	v_add_f32_e32 v9, v38, v9
	v_add_f32_e32 v9, v39, v9
	ds_bpermute_b32 v11, v18, v9
	s_waitcnt lgkmcnt(0)
	v_add_f32_e32 v9, v9, v11
	ds_bpermute_b32 v11, v19, v9
	s_waitcnt lgkmcnt(0)
	v_add_f32_e32 v9, v9, v11
	ds_bpermute_b32 v11, v20, v9
	s_waitcnt lgkmcnt(0)
	v_add_f32_e32 v9, v9, v11
	ds_bpermute_b32 v11, v21, v9
	s_waitcnt lgkmcnt(0)
	v_add_f32_e32 v9, v9, v11
	ds_bpermute_b32 v11, v22, v9
	s_waitcnt lgkmcnt(0)
	v_add_f32_e32 v9, v9, v11
	ds_bpermute_b32 v11, v23, v9
	s_waitcnt lgkmcnt(0)
	v_add_f32_e32 v9, v9, v11
	v_mul_f32_e32 v16, 0x3a800000, v9
	v_pk_add_f32 v[24:25], v[24:25], v[16:17] op_sel_hi:[1,0] neg_lo:[0,1] neg_hi:[0,1]
	v_pk_add_f32 v[26:27], v[26:27], v[16:17] op_sel_hi:[1,0] neg_lo:[0,1] neg_hi:[0,1]
	v_pk_mul_f32 v[52:53], v[24:25], v[24:25]
	v_pk_add_f32 v[30:31], v[30:31], v[16:17] op_sel_hi:[1,0] neg_lo:[0,1] neg_hi:[0,1]
	v_pk_add_f32 v[28:29], v[28:29], v[16:17] op_sel_hi:[1,0] neg_lo:[0,1] neg_hi:[0,1]
	v_pk_add_f32 v[34:35], v[34:35], v[16:17] op_sel_hi:[1,0] neg_lo:[0,1] neg_hi:[0,1]
	v_pk_add_f32 v[32:33], v[32:33], v[16:17] op_sel_hi:[1,0] neg_lo:[0,1] neg_hi:[0,1]
	v_pk_add_f32 v[38:39], v[38:39], v[16:17] op_sel_hi:[1,0] neg_lo:[0,1] neg_hi:[0,1]
	v_pk_add_f32 v[36:37], v[36:37], v[16:17] op_sel_hi:[1,0] neg_lo:[0,1] neg_hi:[0,1]
	v_pk_mul_f32 v[16:17], v[26:27], v[26:27]
	v_add_f32_e32 v9, v52, v53
	v_add_f32_e32 v9, v16, v9
	v_pk_mul_f32 v[56:57], v[28:29], v[28:29]
	v_add_f32_e32 v9, v17, v9
	v_add_f32_e32 v9, v56, v9
	v_pk_mul_f32 v[54:55], v[30:31], v[30:31]
	v_add_f32_e32 v9, v57, v9
	v_add_f32_e32 v9, v54, v9
	v_pk_mul_f32 v[60:61], v[32:33], v[32:33]
	v_add_f32_e32 v9, v55, v9
	v_add_f32_e32 v9, v60, v9
	v_pk_mul_f32 v[58:59], v[34:35], v[34:35]
	v_add_f32_e32 v9, v61, v9
	v_add_f32_e32 v9, v58, v9
	v_pk_mul_f32 v[64:65], v[36:37], v[36:37]
	v_add_f32_e32 v9, v59, v9
	v_add_f32_e32 v9, v64, v9
	v_pk_mul_f32 v[62:63], v[38:39], v[38:39]
	v_add_f32_e32 v9, v65, v9
	v_add_f32_e32 v9, v62, v9
	v_add_f32_e32 v9, v63, v9
	ds_bpermute_b32 v11, v18, v9
	v_lshl_add_u64 v[52:53], v[2:3], 0, v[14:15]
	s_waitcnt lgkmcnt(0)
	v_add_f32_e32 v9, v9, v11
	ds_bpermute_b32 v11, v19, v9
	s_waitcnt lgkmcnt(0)
	v_add_f32_e32 v9, v9, v11
	ds_bpermute_b32 v11, v20, v9
	s_waitcnt lgkmcnt(0)
	v_add_f32_e32 v9, v9, v11
	ds_bpermute_b32 v11, v21, v9
	s_waitcnt lgkmcnt(0)
	v_add_f32_e32 v9, v9, v11
	ds_bpermute_b32 v11, v22, v9
	s_waitcnt lgkmcnt(0)
	v_add_f32_e32 v11, v9, v11
	ds_bpermute_b32 v13, v23, v11
	v_mov_b32_e32 v9, v1
	s_waitcnt lgkmcnt(0)
	v_add_f32_e32 v11, v11, v13
	v_fmamk_f32 v11, v11, 0x3a800000, v208
	v_mul_f32_e32 v13, 0x4b800000, v11
	v_cmp_gt_f32_e32 vcc, s5, v11
	s_nop 1
	v_cndmask_b32_e32 v11, v11, v13, vcc
	v_rsq_f32_e32 v11, v11
	v_mov_b32_e32 v13, v1
	v_mul_f32_e32 v9, 0x45800000, v11
	v_cndmask_b32_e32 v98, v11, v9, vcc
	v_cmp_lt_i32_e32 vcc, s1, v4
	s_or_b64 s[12:13], vcc, s[12:13]
	s_waitcnt vmcnt(0)
	v_pk_mul_f32 v[24:25], v[24:25], v[98:99] op_sel_hi:[1,0]
	v_pk_mul_f32 v[26:27], v[26:27], v[98:99] op_sel_hi:[1,0]
	v_pk_add_f32 v[40:41], v[40:41], 1.0 op_sel_hi:[1,0]
	v_pk_add_f32 v[42:43], v[42:43], 1.0 op_sel_hi:[1,0]
	v_pk_fma_f32 v[40:41], v[40:41], v[24:25], v[44:45]
	v_pk_fma_f32 v[42:43], v[42:43], v[26:27], v[46:47]
	v_cvt_pk_bf16_f32 v40, v40, v41
	v_cvt_pk_bf16_f32 v41, v42, v43
	global_store_dwordx2 v[52:53], v[40:41], off
	v_pk_mul_f32 v[28:29], v[28:29], v[98:99] op_sel_hi:[1,0]
	v_pk_mul_f32 v[30:31], v[30:31], v[98:99] op_sel_hi:[1,0]
	v_pk_add_f32 v[66:67], v[66:67], 1.0 op_sel_hi:[1,0]
	v_pk_add_f32 v[68:69], v[68:69], 1.0 op_sel_hi:[1,0]
	v_pk_fma_f32 v[66:67], v[66:67], v[28:29], v[78:79]
	v_pk_fma_f32 v[68:69], v[68:69], v[30:31], v[80:81]
	v_cvt_pk_bf16_f32 v66, v66, v67
	v_cvt_pk_bf16_f32 v67, v68, v69
	global_store_dwordx2 v[52:53], v[66:67], off offset:512
	v_pk_mul_f32 v[32:33], v[32:33], v[98:99] op_sel_hi:[1,0]
	v_pk_mul_f32 v[34:35], v[34:35], v[98:99] op_sel_hi:[1,0]
	v_pk_add_f32 v[70:71], v[70:71], 1.0 op_sel_hi:[1,0]
	v_pk_add_f32 v[72:73], v[72:73], 1.0 op_sel_hi:[1,0]
	v_pk_fma_f32 v[70:71], v[70:71], v[32:33], v[82:83]
	v_pk_fma_f32 v[72:73], v[72:73], v[34:35], v[84:85]
	v_cvt_pk_bf16_f32 v70, v70, v71
	v_cvt_pk_bf16_f32 v71, v72, v73
	global_store_dwordx2 v[52:53], v[70:71], off offset:1024
	v_pk_mul_f32 v[36:37], v[36:37], v[98:99] op_sel_hi:[1,0]
	v_pk_mul_f32 v[38:39], v[38:39], v[98:99] op_sel_hi:[1,0]
	v_pk_add_f32 v[74:75], v[74:75], 1.0 op_sel_hi:[1,0]
	v_pk_add_f32 v[76:77], v[76:77], 1.0 op_sel_hi:[1,0]
	v_pk_fma_f32 v[74:75], v[74:75], v[36:37], v[86:87]
	v_pk_fma_f32 v[76:77], v[76:77], v[38:39], v[88:89]
	v_cvt_pk_bf16_f32 v74, v74, v75
	v_cvt_pk_bf16_f32 v75, v76, v77
	global_store_dwordx2 v[52:53], v[74:75], off offset:1536
	s_andn2_b64 exec, exec, s[12:13]
	s_cbranch_execz .LBB0_686
